# attention: drop redundant self-max canonicalisations in the row-max tree
# baseline (speedup 1.0000x reference)
; DI void phase_attn(const Params& p, int l, LAS char* lds) {
;     ...
;             __builtin_amdgcn_s_setprio(1);
;             float mx = s0[0];
; #pragma unroll
;             for (int r = 1; r < 16; ++r) mx = fmaxf(mx, s0[r]);
; #pragma unroll
;             for (int r = 0; r < 16; ++r) mx = fmaxf(mx, s1[r]);
;             {
;                 const auto rr = __builtin_amdgcn_permlane32_swap(__float_as_uint(mx), __float_as_uint(mx), false, false);
;                 mx = fmaxf(__uint_as_float(rr[0]), __uint_as_float(rr[1]));
;             }
;             float m_new = m_run;
;             if (__builtin_amdgcn_ballot_w64(mx - m_run > 8.f) != 0ull) {
;                 m_new = fmaxf(m_run, mx);
;                 const float alpha = __builtin_amdgcn_exp2f(m_run - m_new);
;                 m_run = m_new;
;                 l_run *= alpha;
; #pragma unroll
;                 for (int r = 0; r < 16; ++r) { o0[r] *= alpha; o1[r] *= alpha; }
;             }
.LBB0_290:
	s_or_b64 exec, exec, s[52:53]
	s_setprio 1
	s_nop 4
	v_max_f32_e32 v1, v34, v35
	v_max3_f32 v1, v1, v36, v37
	v_max3_f32 v1, v1, v38, v39
	v_max3_f32 v1, v1, v40, v41
	v_max3_f32 v1, v1, v42, v43
	v_max3_f32 v1, v1, v44, v45
	v_max3_f32 v1, v1, v46, v47
	v_max3_f32 v1, v1, v48, v49
	v_max3_f32 v1, v1, v50, v51
	v_max3_f32 v1, v1, v52, v53
	v_max3_f32 v1, v1, v54, v55
	v_max3_f32 v1, v1, v56, v57
	v_max3_f32 v1, v1, v58, v59
	v_max3_f32 v1, v1, v60, v61
	v_max3_f32 v1, v1, v62, v63
	v_max3_f32 v1, v1, v64, v65
	v_mov_b32_e32 v183, v1
	s_nop 1
	v_permlane32_swap_b32_e32 v1, v183
	v_max_f32_e32 v1, v1, v183
	v_sub_f32_e32 v183, v1, v182
	s_mov_b32 s4, 0x41000000
	v_cmp_lt_f32_e32 vcc, s4, v183
	s_cbranch_vccz .LBB0_292
	v_max_f32_e32 v1, v1, v1
	v_max_f32_e32 v183, v182, v182
	v_max_f32_e32 v1, v183, v1
	v_sub_f32_e32 v182, v182, v1
	v_exp_f32_e32 v182, v182
	s_nop 0
	v_pk_mul_f32 v[32:33], v[32:33], v[182:183] op_sel_hi:[1,0]
	v_pk_mul_f32 v[30:31], v[30:31], v[182:183] op_sel_hi:[1,0]
	v_pk_mul_f32 v[28:29], v[28:29], v[182:183] op_sel_hi:[1,0]
	v_pk_mul_f32 v[26:27], v[26:27], v[182:183] op_sel_hi:[1,0]
	v_pk_mul_f32 v[24:25], v[24:25], v[182:183] op_sel_hi:[1,0]
	v_pk_mul_f32 v[22:23], v[22:23], v[182:183] op_sel_hi:[1,0]
	v_pk_mul_f32 v[20:21], v[20:21], v[182:183] op_sel_hi:[1,0]
	v_pk_mul_f32 v[18:19], v[18:19], v[182:183] op_sel_hi:[1,0]
	v_pk_mul_f32 v[16:17], v[16:17], v[182:183] op_sel_hi:[1,0]
	v_pk_mul_f32 v[14:15], v[14:15], v[182:183] op_sel_hi:[1,0]
	v_pk_mul_f32 v[12:13], v[12:13], v[182:183] op_sel_hi:[1,0]
	v_pk_mul_f32 v[10:11], v[10:11], v[182:183] op_sel_hi:[1,0]
	v_pk_mul_f32 v[8:9], v[8:9], v[182:183] op_sel_hi:[1,0]
	v_pk_mul_f32 v[6:7], v[6:7], v[182:183] op_sel_hi:[1,0]
	v_pk_mul_f32 v[4:5], v[4:5], v[182:183] op_sel_hi:[1,0]
	v_pk_mul_f32 v[2:3], v[2:3], v[182:183] op_sel_hi:[1,0]
	v_mul_f32_e32 v181, v181, v182
	v_mov_b32_e32 v182, v1
